# v16 + write-through (sc0 sc1) on the weight-transpose bf16 stores in the MLP-up GEMM tail
# baseline (speedup 1.0000x reference)
; #define LAS __attribute__((address_space(3)))
; __device__ __forceinline__ void transpose_item(const float* W, int K, int N, bf16_t* WT, int ldw, LAS float* scr, int item, int lane) {
;     const int nblk = N / 32, kb = item / nblk, nb = item % nblk, k0 = 64 * kb, n0 = 32 * nb;
;     float tv[32];
; #pragma unroll
;     for (int i = 0; i < 32; ++i) { const int kk = 2 * i + (lane >> 5); tv[i] = W[(size_t)(k0 + kk) * N + n0 + (lane & 31)]; }
; __device__ __forceinline__ void transpose_layers(const Args& a, LAS unsigned char* lds, int l_lo, int l_hi, int wb, int nwb) {
;     ...
;     for (int it = l_lo * I_L + gw; it < l_hi * I_L; it += ngw) {
;         const int l = it / I_L; int r = it % I_L;
;         unsigned char* wl = a.ws + WS_WT + (size_t)l * WT_LAYER;
;         if (r < I_IN) { transpose_item(a.in[8] + (size_t)l * DM * DIN, DM, DIN, (bf16_t*)(wl + WT_IN), DM, scr, r, lane); continue; } r -= I_IN;
;         if (r < I_OUT) { transpose_item(a.in[26] + (size_t)l * DM * DM, DM, DM, (bf16_t*)(wl + WT_OUT), DM, scr, r, lane); continue; } r -= I_OUT;
;         if (r < I_1) { transpose_item(a.in[27] + (size_t)l * DM * DFF, DM, DFF, (bf16_t*)(wl + WT_1), DM, scr, r, lane); continue; } r -= I_1;
;         transpose_item(a.in[28] + (size_t)l * DFF * DM, DFF, DM, (bf16_t*)(wl + WT_2), HP, scr, r, lane);
.LBB0_202:
	s_mov_b32 s28, 0x2fa0be83
	v_mul_hi_i32 v4, v3, s28
	v_lshrrev_b32_e32 v5, 31, v4
	v_ashrrev_i32_e32 v4, 10, v4
	v_readlane_b32 s28, v252, 33
	v_add_u32_e32 v6, v4, v5
	v_readlane_b32 s29, v252, 34
	v_mul_i32_i24_e32 v8, 0x1580, v6
	v_sub_u32_e32 v9, v3, v8
	v_mov_b64_e32 v[4:5], s[28:29]
	s_mov_b32 s28, 0x1580000
	v_mad_i64_i32 v[4:5], s[34:35], v6, s28, v[4:5]
	s_movk_i32 s28, 0x37f
	v_ashrrev_i32_e32 v7, 31, v6
	v_cmp_lt_i32_e32 vcc, s28, v9
	s_and_saveexec_b64 s[34:35], vcc
	s_xor_b64 s[38:39], exec, s[34:35]
	s_cbranch_execz .LBB0_212
	s_movk_i32 s28, 0x57f
	v_cmp_lt_u32_e32 vcc, s28, v9
	s_and_saveexec_b64 s[34:35], vcc
	s_xor_b64 s[40:41], exec, s[34:35]
	s_cbranch_execz .LBB0_209
	s_movk_i32 s28, 0xd7f
	v_cmp_lt_u32_e32 vcc, s28, v9
	v_lshlrev_b64 v[6:7], 24, v[6:7]
	s_and_saveexec_b64 s[34:35], vcc
	s_xor_b64 s[44:45], exec, s[34:35]
	s_cbranch_execz .LBB0_206
	v_readlane_b32 s68, v251, 0
	v_readlane_b32 s76, v251, 8
	v_readlane_b32 s77, v251, 9
	v_and_b32_e32 v23, 31, v9
	v_add_u32_e32 v8, 0xf280, v9
	v_lshl_add_u64 v[6:7], s[76:77], 0, v[6:7]
	v_lshlrev_b32_e32 v206, 7, v23
	v_bfe_u32 v8, v8, 5, 11
	v_lshl_add_u64 v[6:7], v[6:7], 0, v[206:207]
	v_lshlrev_b32_e32 v206, 2, v2
	v_lshlrev_b32_e32 v23, 2, v17
	v_lshl_add_u64 v[6:7], v[6:7], 0, v[206:207]
	v_lshl_or_b32 v206, v8, 18, v23
	v_lshl_add_u64 v[6:7], v[6:7], 0, v[206:207]
	s_movk_i32 s28, 0x2000
	v_add_co_u32_e32 v24, vcc, s28, v6
	s_movk_i32 s28, 0x4000
	s_nop 0
	v_addc_co_u32_e32 v25, vcc, 0, v7, vcc
	global_load_dword v23, v[6:7], off
	global_load_dword v26, v[24:25], off
	v_add_co_u32_e32 v24, vcc, s28, v6
	s_mov_b32 s28, 0x8000
	s_nop 0
	v_addc_co_u32_e32 v25, vcc, 0, v7, vcc
	global_load_dword v27, v[24:25], off
	v_add_co_u32_e32 v24, vcc, s7, v6
	s_mov_b64 s[8:9], 0xd80000
	s_nop 0
	v_addc_co_u32_e32 v25, vcc, 0, v7, vcc
	global_load_dword v28, v[24:25], off
	v_add_co_u32_e32 v24, vcc, s28, v6
	s_mov_b32 s28, 0xa000
	s_nop 0
	v_addc_co_u32_e32 v25, vcc, 0, v7, vcc
	global_load_dword v29, v[24:25], off
	v_add_co_u32_e32 v24, vcc, s28, v6
	s_mov_b32 s28, 0xc000
	s_nop 0
	v_addc_co_u32_e32 v25, vcc, 0, v7, vcc
	global_load_dword v30, v[24:25], off
	v_add_co_u32_e32 v24, vcc, s28, v6
	s_mov_b32 s28, 0xe000
	s_nop 0
	v_addc_co_u32_e32 v25, vcc, 0, v7, vcc
	global_load_dword v31, v[24:25], off
	v_add_co_u32_e32 v24, vcc, s28, v6
	s_mov_b32 s28, 0x10000
	s_nop 0
	v_addc_co_u32_e32 v25, vcc, 0, v7, vcc
	global_load_dword v32, v[24:25], off
	v_add_co_u32_e32 v24, vcc, s28, v6
	s_mov_b32 s28, 0x12000
	s_nop 0
	v_addc_co_u32_e32 v25, vcc, 0, v7, vcc
	global_load_dword v33, v[24:25], off
	v_add_co_u32_e32 v24, vcc, s28, v6
	s_mov_b32 s28, 0x14000
	s_nop 0
	v_addc_co_u32_e32 v25, vcc, 0, v7, vcc
	global_load_dword v34, v[24:25], off
	v_add_co_u32_e32 v24, vcc, s28, v6
	s_mov_b32 s28, 0x16000
	s_nop 0
	v_addc_co_u32_e32 v25, vcc, 0, v7, vcc
	global_load_dword v35, v[24:25], off
	v_add_co_u32_e32 v24, vcc, s28, v6
	s_mov_b32 s28, 0x18000
	s_nop 0
	v_addc_co_u32_e32 v25, vcc, 0, v7, vcc
	global_load_dword v36, v[24:25], off
	v_add_co_u32_e32 v24, vcc, s28, v6
	s_mov_b32 s28, 0x1a000
	s_nop 0
	v_addc_co_u32_e32 v25, vcc, 0, v7, vcc
	global_load_dword v37, v[24:25], off
	v_add_co_u32_e32 v24, vcc, s28, v6
	s_mov_b32 s28, 0x1c000
	s_nop 0
	v_addc_co_u32_e32 v25, vcc, 0, v7, vcc
	global_load_dword v38, v[24:25], off
	v_add_co_u32_e32 v24, vcc, s28, v6
	s_mov_b32 s28, 0x20000
	s_nop 0
	v_addc_co_u32_e32 v25, vcc, 0, v7, vcc
	global_load_dword v39, v[24:25], off
	v_add_co_u32_e32 v24, vcc, s26, v6
	v_lshl_add_u64 v[4:5], v[4:5], 0, s[8:9]
	s_nop 0
	v_addc_co_u32_e32 v25, vcc, 0, v7, vcc
	global_load_dword v40, v[24:25], off
	v_add_co_u32_e32 v24, vcc, s28, v6
	s_mov_b32 s28, 0x22000
	s_nop 0
	v_addc_co_u32_e32 v25, vcc, 0, v7, vcc
	global_load_dword v41, v[24:25], off
	v_add_co_u32_e32 v24, vcc, s28, v6
	s_mov_b32 s28, 0x24000
	s_nop 0
	v_addc_co_u32_e32 v25, vcc, 0, v7, vcc
	global_load_dword v42, v[24:25], off
	v_add_co_u32_e32 v24, vcc, s28, v6
	s_mov_b32 s28, 0x26000
	s_nop 0
	v_addc_co_u32_e32 v25, vcc, 0, v7, vcc
	global_load_dword v43, v[24:25], off
	v_add_co_u32_e32 v24, vcc, s28, v6
	s_mov_b32 s28, 0x28000
	s_nop 0
	v_addc_co_u32_e32 v25, vcc, 0, v7, vcc
	global_load_dword v44, v[24:25], off
	v_add_co_u32_e32 v24, vcc, s28, v6
	s_mov_b32 s28, 0x2a000
	s_nop 0
	v_addc_co_u32_e32 v25, vcc, 0, v7, vcc
	global_load_dword v45, v[24:25], off
	v_add_co_u32_e32 v24, vcc, s28, v6
	s_mov_b32 s28, 0x2c000
	s_nop 0
	v_addc_co_u32_e32 v25, vcc, 0, v7, vcc
	global_load_dword v46, v[24:25], off
	v_add_co_u32_e32 v24, vcc, s28, v6
	s_mov_b32 s28, 0x2e000
	s_nop 0
	v_addc_co_u32_e32 v25, vcc, 0, v7, vcc
	global_load_dword v47, v[24:25], off
	v_add_co_u32_e32 v24, vcc, s28, v6
	s_mov_b32 s28, 0x30000
	s_nop 0
	v_addc_co_u32_e32 v25, vcc, 0, v7, vcc
	global_load_dword v48, v[24:25], off
	v_add_co_u32_e32 v24, vcc, s28, v6
	s_mov_b32 s28, 0x32000
	s_nop 0
	v_addc_co_u32_e32 v25, vcc, 0, v7, vcc
	global_load_dword v49, v[24:25], off
	v_add_co_u32_e32 v24, vcc, s28, v6
	s_mov_b32 s28, 0x34000
	s_nop 0
	v_addc_co_u32_e32 v25, vcc, 0, v7, vcc
	global_load_dword v50, v[24:25], off
	v_add_co_u32_e32 v24, vcc, s28, v6
	s_mov_b32 s28, 0x36000
	s_nop 0
	v_addc_co_u32_e32 v25, vcc, 0, v7, vcc
	global_load_dword v51, v[24:25], off
	v_add_co_u32_e32 v24, vcc, s28, v6
	s_mov_b32 s28, 0x38000
	s_nop 0
	v_addc_co_u32_e32 v25, vcc, 0, v7, vcc
	global_load_dword v52, v[24:25], off
	v_add_co_u32_e32 v24, vcc, s28, v6
	s_mov_b32 s28, 0x3a000
	s_nop 0
	v_addc_co_u32_e32 v25, vcc, 0, v7, vcc
	global_load_dword v53, v[24:25], off
	v_add_co_u32_e32 v24, vcc, s28, v6
	s_mov_b32 s28, 0x3c000
	s_nop 0
	v_addc_co_u32_e32 v25, vcc, 0, v7, vcc
	global_load_dword v54, v[24:25], off
	v_add_co_u32_e32 v24, vcc, s28, v6
	s_mov_b32 s28, 0x3e000
	s_nop 0
	v_addc_co_u32_e32 v25, vcc, 0, v7, vcc
	v_add_co_u32_e32 v6, vcc, s28, v6
	global_load_dword v24, v[24:25], off
	s_nop 0
	v_addc_co_u32_e32 v7, vcc, 0, v7, vcc
	global_load_dword v6, v[6:7], off
	v_add_u32_e32 v7, 0x400, v11
	s_waitcnt vmcnt(0)
; #define LAS __attribute__((address_space(3)))
; __device__ __forceinline__ unsigned pk2(float lo, float hi) { return f2bf(lo) | (f2bf(hi) << 16); }
; __host__ __device__ __forceinline__ unsigned img_off(unsigned row, unsigned col, unsigned KT) { return (((row >> 8) * KT + (col >> 6)) << 14) + (((row >> 7) & 1u) << 13) + hl_off(row & 127u, col & 63u); }
; __host__ __device__ __forceinline__ unsigned wrow_img(unsigned n) { const unsigned p = n & 31u, rho = 16u * ((p >> 2) & 1u) + 4u * (p >> 3) + (p & 3u); return (n & ~31u) | rho; }
; __device__ __forceinline__ void transpose_item(const float* W, int K, int N, bf16_t* WT, int ldw, LAS float* scr, int item, int lane) {
;     ...
;     for (int i = 0; i < 32; ++i) { const int kk = 2 * i + (lane >> 5); scr[kk * 33 + (lane & 31)] = tv[i]; }
;     asm volatile("s_waitcnt lgkmcnt(0)" ::: "memory");
;     const int c = lane & 7;
; #pragma unroll
;     for (int j = 0; j < 4; ++j) { const int n = (lane >> 3) + 8 * j; const LAS float* s = scr + (8 * c) * 33 + n;
;         u32x4 o; o.x = pk2(s[0 * 33], s[1 * 33]); o.y = pk2(s[2 * 33], s[3 * 33]); o.z = pk2(s[4 * 33], s[5 * 33]); o.w = pk2(s[6 * 33], s[7 * 33]);
;         *(u32x4*)(WT + img_off(wrow_img((unsigned)(n0 + n)), (unsigned)(k0 + 8 * c), (unsigned)(K / 64))) = o; }
	ds_write2_b32 v11, v23, v26 offset1:66
	ds_write2_b32 v11, v27, v28 offset0:132 offset1:198
	ds_write2_b32 v7, v29, v30 offset0:8 offset1:74
	ds_write2_b32 v7, v31, v32 offset0:140 offset1:206
	v_add_u32_e32 v7, 0x800, v11
	ds_write2_b32 v7, v33, v34 offset0:16 offset1:82
	ds_write2_b32 v7, v35, v36 offset0:148 offset1:214
	v_add_u32_e32 v7, 0xc00, v11
	ds_write2_b32 v7, v37, v38 offset0:24 offset1:90
	ds_write2_b32 v7, v39, v40 offset0:156 offset1:222
	v_add_u32_e32 v7, 0x1000, v11
	ds_write2_b32 v7, v41, v42 offset0:32 offset1:98
	ds_write2_b32 v7, v43, v44 offset0:164 offset1:230
	v_add_u32_e32 v7, 0x1400, v11
	ds_write2_b32 v7, v45, v46 offset0:40 offset1:106
	ds_write2_b32 v7, v47, v48 offset0:172 offset1:238
	v_add_u32_e32 v7, 0x1800, v11
	ds_write2_b32 v7, v49, v50 offset0:48 offset1:114
	ds_write2_b32 v7, v51, v52 offset0:180 offset1:246
	v_add_u32_e32 v7, 0x1c00, v11
	ds_write2_b32 v7, v53, v54 offset0:56 offset1:122
	ds_write2_b32 v7, v24, v6 offset0:188 offset1:254
	v_lshlrev_b32_e32 v6, 3, v9
	s_waitcnt lgkmcnt(0)
	v_and_b32_e32 v6, 0xc0, v6
	v_add_u32_e32 v8, v8, v6
	ds_read2_b32 v[6:7], v12 offset0:33 offset1:41
	ds_read2_b32 v[28:29], v12 offset1:8
	ds_read2_b32 v[30:31], v12 offset0:66 offset1:74
	ds_read2_b32 v[32:33], v12 offset0:99 offset1:107
	ds_read2_b32 v[34:35], v12 offset0:132 offset1:140
	ds_read2_b32 v[36:37], v12 offset0:165 offset1:173
	ds_read2_b32 v[38:39], v12 offset0:198 offset1:206
	ds_read2_b32 v[40:41], v12 offset0:231 offset1:239
	s_waitcnt lgkmcnt(7)
	v_bfe_u32 v25, v6, 16, 1
	s_waitcnt lgkmcnt(6)
	v_bfe_u32 v24, v28, 16, 1
	v_add3_u32 v24, v28, v24, s27
	v_lshrrev_b32_e32 v24, 16, v24
	v_add3_u32 v6, v6, v25, s27
	v_and_or_b32 v24, v6, s6, v24
	s_waitcnt lgkmcnt(5)
	v_bfe_u32 v6, v30, 16, 1
	v_add3_u32 v6, v30, v6, s27
	s_waitcnt lgkmcnt(4)
	v_bfe_u32 v25, v32, 16, 1
	v_lshrrev_b32_e32 v6, 16, v6
	v_add3_u32 v25, v32, v25, s27
	v_and_or_b32 v25, v25, s6, v6
	s_waitcnt lgkmcnt(3)
	v_bfe_u32 v6, v34, 16, 1
	v_add3_u32 v6, v34, v6, s27
	s_waitcnt lgkmcnt(2)
	v_bfe_u32 v26, v36, 16, 1
	v_lshrrev_b32_e32 v6, 16, v6
	v_add3_u32 v26, v36, v26, s27
	v_and_or_b32 v26, v26, s6, v6
	s_waitcnt lgkmcnt(1)
	v_bfe_u32 v6, v38, 16, 1
	v_add3_u32 v6, v38, v6, s27
	s_waitcnt lgkmcnt(0)
	v_bfe_u32 v27, v40, 16, 1
	v_lshrrev_b32_e32 v6, 16, v6
	v_add3_u32 v27, v40, v27, s27
	v_and_or_b32 v27, v27, s6, v6
	v_lshlrev_b32_e32 v6, 11, v9
	v_lshl_or_b32 v23, v9, 5, v13
	v_and_b32_e32 v6, 0x2000, v6
	v_lshl_or_b32 v6, v8, 14, v6
	v_lshrrev_b32_e32 v8, 3, v23
	v_and_or_b32 v8, v8, 14, v14
	v_lshl_or_b32 v23, v8, 9, v6
	v_or_b32_e32 v6, v23, v18
	v_lshlrev_b32_e32 v206, 1, v6
	v_bfe_u32 v6, v29, 16, 1
	v_add3_u32 v6, v29, v6, s27
	v_bfe_u32 v8, v7, 16, 1
	v_lshrrev_b32_e32 v6, 16, v6
	v_add3_u32 v7, v7, v8, s27
	v_and_or_b32 v6, v7, s6, v6
	v_bfe_u32 v7, v31, 16, 1
	v_add3_u32 v7, v31, v7, s27
	v_bfe_u32 v8, v33, 16, 1
	v_lshrrev_b32_e32 v7, 16, v7
	v_add3_u32 v8, v33, v8, s27
	v_and_or_b32 v7, v8, s6, v7
	v_bfe_u32 v8, v35, 16, 1
	v_add3_u32 v8, v35, v8, s27
	v_bfe_u32 v9, v37, 16, 1
	v_lshrrev_b32_e32 v8, 16, v8
	v_add3_u32 v9, v37, v9, s27
	v_lshl_add_u64 v[42:43], v[4:5], 0, v[206:207]
	v_and_or_b32 v8, v9, s6, v8
	v_bfe_u32 v9, v39, 16, 1
	global_store_dwordx4 v[42:43], v[24:27], off sc0 sc1
	v_add3_u32 v9, v39, v9, s27
	v_lshrrev_b32_e32 v9, 16, v9
	v_bfe_u32 v24, v41, 16, 1
	v_add3_u32 v24, v41, v24, s27
	v_and_or_b32 v9, v24, s6, v9
	global_store_dwordx4 v[42:43], v[6:9], off offset:256 sc0 sc1
	ds_read2_b32 v[24:25], v12 offset0:49 offset1:57
	ds_read2_b32 v[26:27], v12 offset0:16 offset1:24
	ds_read2_b32 v[28:29], v12 offset0:82 offset1:90
	ds_read2_b32 v[30:31], v12 offset0:115 offset1:123
	ds_read2_b32 v[32:33], v12 offset0:148 offset1:156
	ds_read2_b32 v[34:35], v12 offset0:181 offset1:189
	ds_read2_b32 v[36:37], v12 offset0:214 offset1:222
	ds_read2_b32 v[38:39], v12 offset0:247 offset1:255
	s_waitcnt lgkmcnt(7)
	v_bfe_u32 v7, v24, 16, 1
	s_waitcnt lgkmcnt(6)
	v_bfe_u32 v6, v26, 16, 1
	v_add3_u32 v6, v26, v6, s27
	v_lshrrev_b32_e32 v6, 16, v6
	v_add3_u32 v7, v24, v7, s27
	v_and_or_b32 v6, v7, s6, v6
	s_waitcnt lgkmcnt(5)
	v_bfe_u32 v7, v28, 16, 1
	v_add3_u32 v7, v28, v7, s27
	s_waitcnt lgkmcnt(4)
	v_bfe_u32 v8, v30, 16, 1
	v_lshrrev_b32_e32 v7, 16, v7
	v_add3_u32 v8, v30, v8, s27
	v_and_or_b32 v7, v8, s6, v7
	s_waitcnt lgkmcnt(3)
	v_bfe_u32 v8, v32, 16, 1
	v_add3_u32 v8, v32, v8, s27
	s_waitcnt lgkmcnt(2)
	v_bfe_u32 v9, v34, 16, 1
	v_lshrrev_b32_e32 v8, 16, v8
	v_add3_u32 v9, v34, v9, s27
	v_and_or_b32 v8, v9, s6, v8
	s_waitcnt lgkmcnt(1)
	v_bfe_u32 v9, v36, 16, 1
	v_add3_u32 v9, v36, v9, s27
	s_waitcnt lgkmcnt(0)
	v_bfe_u32 v24, v38, 16, 1
	s_movk_i32 s28, 0x110
	v_lshrrev_b32_e32 v9, 16, v9
	v_add3_u32 v24, v38, v24, s27
	v_bitop3_b32 v206, v23, s28, v18 bitop3:0x36
	v_and_or_b32 v9, v24, s6, v9
	v_lshl_add_u64 v[40:41], v[206:207], 1, v[4:5]
	global_store_dwordx4 v[40:41], v[6:9], off sc0 sc1
	v_bfe_u32 v24, v39, 16, 1
	s_movk_i32 s28, 0x190
	v_bfe_u32 v6, v27, 16, 1
	v_add3_u32 v6, v27, v6, s27
	v_bfe_u32 v7, v25, 16, 1
	v_lshrrev_b32_e32 v6, 16, v6
	v_add3_u32 v7, v25, v7, s27
	v_and_or_b32 v6, v7, s6, v6
	v_bfe_u32 v7, v29, 16, 1
	v_add3_u32 v7, v29, v7, s27
	v_bfe_u32 v8, v31, 16, 1
	v_lshrrev_b32_e32 v7, 16, v7
	v_add3_u32 v8, v31, v8, s27
	v_and_or_b32 v7, v8, s6, v7
	v_bfe_u32 v8, v33, 16, 1
	v_add3_u32 v8, v33, v8, s27
	v_bfe_u32 v9, v35, 16, 1
	v_lshrrev_b32_e32 v8, 16, v8
	v_add3_u32 v9, v35, v9, s27
	v_and_or_b32 v8, v9, s6, v8
	v_bfe_u32 v9, v37, 16, 1
	v_add3_u32 v9, v37, v9, s27
	v_lshrrev_b32_e32 v9, 16, v9
	v_add3_u32 v24, v39, v24, s27
	v_bitop3_b32 v206, v23, s28, v18 bitop3:0x36
	v_and_or_b32 v9, v24, s6, v9
	v_lshl_add_u64 v[4:5], v[206:207], 1, v[4:5]
	global_store_dwordx4 v[4:5], v[6:9], off sc0 sc1
	s_waitcnt lgkmcnt(0)
	v_readlane_b32 s69, v251, 1
	v_readlane_b32 s70, v251, 2
	v_readlane_b32 s71, v251, 3
	v_readlane_b32 s72, v251, 4
	v_readlane_b32 s73, v251, 5
	v_readlane_b32 s74, v251, 6
	v_readlane_b32 s75, v251, 7
	v_readlane_b32 s78, v251, 10
	v_readlane_b32 s79, v251, 11
	v_readlane_b32 s80, v251, 12
	v_readlane_b32 s81, v251, 13
	v_readlane_b32 s82, v251, 14
	v_readlane_b32 s83, v251, 15
; __device__ __forceinline__ void transpose_item(const float* W, int K, int N, bf16_t* WT, int ldw, LAS float* scr, int item, int lane) {
;     const int nblk = N / 32, kb = item / nblk, nb = item % nblk, k0 = 64 * kb, n0 = 32 * nb;
;     float tv[32];
; #pragma unroll
;     for (int i = 0; i < 32; ++i) { const int kk = 2 * i + (lane >> 5); tv[i] = W[(size_t)(k0 + kk) * N + n0 + (lane & 31)]; }
.LBB0_206:
	s_andn2_saveexec_b64 s[44:45], s[44:45]
	s_cbranch_execz .LBB0_208
	v_lshlrev_b32_e32 v23, 5, v8
	v_readlane_b32 s68, v251, 0
	v_sub_u32_e32 v23, v21, v23
	v_readlane_b32 s74, v251, 6
	v_readlane_b32 s75, v251, 7
	v_and_b32_e32 v24, 0xfe0, v23
	v_add_u32_e32 v9, 0xfa80, v9
	v_lshl_add_u64 v[6:7], s[74:75], 0, v[6:7]
	v_lshlrev_b32_e32 v206, 2, v24
	v_bfe_u32 v9, v9, 7, 9
	v_lshl_add_u64 v[6:7], v[6:7], 0, v[206:207]
	v_lshlrev_b32_e32 v206, 2, v2
	v_lshl_add_u64 v[6:7], v[6:7], 0, v[206:207]
	v_lshl_or_b32 v206, v9, 20, v22
	v_lshl_add_u64 v[6:7], v[6:7], 0, v[206:207]
	s_mov_b32 s28, 0x8000
	v_add_co_u32_e32 v24, vcc, s28, v6
	s_mov_b32 s28, 0x10000
	s_nop 0
	v_addc_co_u32_e32 v25, vcc, 0, v7, vcc
	global_load_dword v26, v[6:7], off
	global_load_dword v27, v[24:25], off
	v_add_co_u32_e32 v24, vcc, s28, v6
	s_mov_b32 s28, 0x18000
	s_nop 0
	v_addc_co_u32_e32 v25, vcc, 0, v7, vcc
	global_load_dword v28, v[24:25], off
	v_add_co_u32_e32 v24, vcc, s28, v6
	s_mov_b32 s28, 0x20000
	s_nop 0
	v_addc_co_u32_e32 v25, vcc, 0, v7, vcc
	global_load_dword v29, v[24:25], off
	v_add_co_u32_e32 v24, vcc, s28, v6
	s_mov_b32 s28, 0x28000
	s_nop 0
	v_addc_co_u32_e32 v25, vcc, 0, v7, vcc
	global_load_dword v30, v[24:25], off
	v_add_co_u32_e32 v24, vcc, s28, v6
	s_mov_b32 s28, 0x30000
	s_nop 0
	v_addc_co_u32_e32 v25, vcc, 0, v7, vcc
	global_load_dword v31, v[24:25], off
	v_add_co_u32_e32 v24, vcc, s28, v6
	s_mov_b32 s28, 0x38000
	s_nop 0
	v_addc_co_u32_e32 v25, vcc, 0, v7, vcc
	global_load_dword v32, v[24:25], off
	v_add_co_u32_e32 v24, vcc, s28, v6
	s_mov_b32 s28, 0x40000
	s_nop 0
	v_addc_co_u32_e32 v25, vcc, 0, v7, vcc
	global_load_dword v33, v[24:25], off
	v_add_co_u32_e32 v24, vcc, s28, v6
	s_mov_b32 s28, 0x48000
	s_nop 0
	v_addc_co_u32_e32 v25, vcc, 0, v7, vcc
	global_load_dword v34, v[24:25], off
	v_add_co_u32_e32 v24, vcc, s28, v6
	s_mov_b32 s28, 0x50000
	s_nop 0
	v_addc_co_u32_e32 v25, vcc, 0, v7, vcc
	global_load_dword v35, v[24:25], off
	v_add_co_u32_e32 v24, vcc, s28, v6
	s_mov_b32 s28, 0x58000
	s_nop 0
	v_addc_co_u32_e32 v25, vcc, 0, v7, vcc
	global_load_dword v36, v[24:25], off
	v_add_co_u32_e32 v24, vcc, s28, v6
	s_mov_b32 s28, 0x68000
	s_nop 0
	v_addc_co_u32_e32 v25, vcc, 0, v7, vcc
	global_load_dword v37, v[24:25], off
	v_add_co_u32_e32 v24, vcc, s33, v6
	v_add_u32_e32 v23, v23, v13
	s_nop 0
	v_addc_co_u32_e32 v25, vcc, 0, v7, vcc
	global_load_dword v38, v[24:25], off
	v_add_co_u32_e32 v24, vcc, s28, v6
	s_mov_b32 s28, 0x70000
	s_nop 0
	v_addc_co_u32_e32 v25, vcc, 0, v7, vcc
	global_load_dword v39, v[24:25], off
	v_add_co_u32_e32 v24, vcc, s28, v6
	s_mov_b32 s28, 0x80000
	s_nop 0
	v_addc_co_u32_e32 v25, vcc, 0, v7, vcc
	global_load_dword v40, v[24:25], off
	v_add_co_u32_e32 v24, vcc, s2, v6
	s_mov_b64 s[8:9], 0x580000
	s_nop 0
	v_addc_co_u32_e32 v25, vcc, 0, v7, vcc
	global_load_dword v41, v[24:25], off
	v_add_co_u32_e32 v24, vcc, s28, v6
	s_mov_b32 s28, 0x88000
	s_nop 0
	v_addc_co_u32_e32 v25, vcc, 0, v7, vcc
	global_load_dword v42, v[24:25], off
	v_add_co_u32_e32 v24, vcc, s28, v6
	s_mov_b32 s28, 0x98000
	s_nop 0
	v_addc_co_u32_e32 v25, vcc, 0, v7, vcc
	global_load_dword v43, v[24:25], off
	v_add_co_u32_e32 v24, vcc, s3, v6
	v_lshl_add_u64 v[4:5], v[4:5], 0, s[8:9]
	s_nop 0
	v_addc_co_u32_e32 v25, vcc, 0, v7, vcc
	global_load_dword v44, v[24:25], off
	v_add_co_u32_e32 v24, vcc, s28, v6
	s_mov_b32 s28, 0xa0000
	s_nop 0
	v_addc_co_u32_e32 v25, vcc, 0, v7, vcc
	global_load_dword v45, v[24:25], off
	v_add_co_u32_e32 v24, vcc, s28, v6
	s_mov_b32 s28, 0xb0000
	s_nop 0
	v_addc_co_u32_e32 v25, vcc, 0, v7, vcc
	global_load_dword v46, v[24:25], off
	v_add_co_u32_e32 v24, vcc, s30, v6
	v_readlane_b32 s69, v251, 1
	s_nop 0
	v_addc_co_u32_e32 v25, vcc, 0, v7, vcc
	global_load_dword v47, v[24:25], off
	v_add_co_u32_e32 v24, vcc, s28, v6
	s_mov_b32 s28, 0xb8000
	s_nop 0
	v_addc_co_u32_e32 v25, vcc, 0, v7, vcc
	global_load_dword v48, v[24:25], off
	v_add_co_u32_e32 v24, vcc, s28, v6
	s_mov_b32 s28, 0xc0000
	s_nop 0
	v_addc_co_u32_e32 v25, vcc, 0, v7, vcc
	global_load_dword v49, v[24:25], off
	v_add_co_u32_e32 v24, vcc, s28, v6
	s_mov_b32 s28, 0xc8000
	s_nop 0
	v_addc_co_u32_e32 v25, vcc, 0, v7, vcc
	global_load_dword v50, v[24:25], off
	v_add_co_u32_e32 v24, vcc, s28, v6
	s_mov_b32 s28, 0xd0000
	s_nop 0
	v_addc_co_u32_e32 v25, vcc, 0, v7, vcc
	global_load_dword v51, v[24:25], off
	v_add_co_u32_e32 v24, vcc, s28, v6
	s_mov_b32 s28, 0xd8000
	s_nop 0
	v_addc_co_u32_e32 v25, vcc, 0, v7, vcc
	global_load_dword v52, v[24:25], off
	v_add_co_u32_e32 v24, vcc, s28, v6
	s_mov_b32 s28, 0xe0000
	s_nop 0
	v_addc_co_u32_e32 v25, vcc, 0, v7, vcc
	global_load_dword v53, v[24:25], off
	v_add_co_u32_e32 v24, vcc, s28, v6
	s_mov_b32 s28, 0xe8000
	s_nop 0
	v_addc_co_u32_e32 v25, vcc, 0, v7, vcc
	global_load_dword v54, v[24:25], off
	v_add_co_u32_e32 v24, vcc, s28, v6
	s_mov_b32 s28, 0xf0000
	s_nop 0
	v_addc_co_u32_e32 v25, vcc, 0, v7, vcc
	global_load_dword v55, v[24:25], off
	v_add_co_u32_e32 v24, vcc, s28, v6
	s_mov_b32 s28, 0xf8000
	s_nop 0
	v_addc_co_u32_e32 v25, vcc, 0, v7, vcc
	v_add_co_u32_e32 v6, vcc, s28, v6
	global_load_dword v24, v[24:25], off
	s_nop 0
	v_addc_co_u32_e32 v7, vcc, 0, v7, vcc
	global_load_dword v6, v[6:7], off
	v_add_u32_e32 v7, 0x400, v11
	s_waitcnt vmcnt(0)
; #define LAS __attribute__((address_space(3)))
; __device__ __forceinline__ unsigned pk2(float lo, float hi) { return f2bf(lo) | (f2bf(hi) << 16); }
; __host__ __device__ __forceinline__ unsigned img_off(unsigned row, unsigned col, unsigned KT) { return (((row >> 8) * KT + (col >> 6)) << 14) + (((row >> 7) & 1u) << 13) + hl_off(row & 127u, col & 63u); }
; __host__ __device__ __forceinline__ unsigned wrow_img(unsigned n) { const unsigned p = n & 31u, rho = 16u * ((p >> 2) & 1u) + 4u * (p >> 3) + (p & 3u); return (n & ~31u) | rho; }
; __device__ __forceinline__ void transpose_item(const float* W, int K, int N, bf16_t* WT, int ldw, LAS float* scr, int item, int lane) {
;     ...
;     for (int i = 0; i < 32; ++i) { const int kk = 2 * i + (lane >> 5); scr[kk * 33 + (lane & 31)] = tv[i]; }
;     asm volatile("s_waitcnt lgkmcnt(0)" ::: "memory");
;     const int c = lane & 7;
; #pragma unroll
;     for (int j = 0; j < 4; ++j) { const int n = (lane >> 3) + 8 * j; const LAS float* s = scr + (8 * c) * 33 + n;
;         u32x4 o; o.x = pk2(s[0 * 33], s[1 * 33]); o.y = pk2(s[2 * 33], s[3 * 33]); o.z = pk2(s[4 * 33], s[5 * 33]); o.w = pk2(s[6 * 33], s[7 * 33]);
;         *(u32x4*)(WT + img_off(wrow_img((unsigned)(n0 + n)), (unsigned)(k0 + 8 * c), (unsigned)(K / 64))) = o; }
	ds_write2_b32 v11, v26, v27 offset1:66
	ds_write2_b32 v11, v28, v29 offset0:132 offset1:198
	ds_write2_b32 v7, v30, v31 offset0:8 offset1:74
	ds_write2_b32 v7, v32, v33 offset0:140 offset1:206
	v_add_u32_e32 v7, 0x800, v11
	ds_write2_b32 v7, v34, v35 offset0:16 offset1:82
	ds_write2_b32 v7, v36, v37 offset0:148 offset1:214
	v_add_u32_e32 v7, 0xc00, v11
	ds_write2_b32 v7, v38, v39 offset0:24 offset1:90
	ds_write2_b32 v7, v40, v41 offset0:156 offset1:222
	v_add_u32_e32 v7, 0x1000, v11
	ds_write2_b32 v7, v42, v43 offset0:32 offset1:98
	ds_write2_b32 v7, v44, v45 offset0:164 offset1:230
	v_add_u32_e32 v7, 0x1400, v11
	ds_write2_b32 v7, v46, v47 offset0:40 offset1:106
	ds_write2_b32 v7, v48, v49 offset0:172 offset1:238
	v_add_u32_e32 v7, 0x1800, v11
	ds_write2_b32 v7, v50, v51 offset0:48 offset1:114
	ds_write2_b32 v7, v52, v53 offset0:180 offset1:246
	v_add_u32_e32 v7, 0x1c00, v11
	ds_write2_b32 v7, v54, v55 offset0:56 offset1:122
	ds_write2_b32 v7, v24, v6 offset0:188 offset1:254
	v_lshlrev_b32_e32 v6, 1, v8
	v_sub_u32_e32 v6, v20, v6
	s_waitcnt lgkmcnt(0)
	v_and_b32_e32 v6, 0xf0, v6
	v_add_u32_e32 v9, v9, v6
	ds_read2_b32 v[6:7], v12 offset0:33 offset1:41
	ds_read2_b32 v[28:29], v12 offset1:8
	ds_read2_b32 v[30:31], v12 offset0:66 offset1:74
	ds_read2_b32 v[32:33], v12 offset0:99 offset1:107
	ds_read2_b32 v[34:35], v12 offset0:132 offset1:140
	ds_read2_b32 v[36:37], v12 offset0:165 offset1:173
	ds_read2_b32 v[38:39], v12 offset0:198 offset1:206
	ds_read2_b32 v[40:41], v12 offset0:231 offset1:239
	s_waitcnt lgkmcnt(7)
	v_bfe_u32 v25, v6, 16, 1
	s_waitcnt lgkmcnt(6)
	v_bfe_u32 v24, v28, 16, 1
	v_add3_u32 v24, v28, v24, s27
	v_lshrrev_b32_e32 v24, 16, v24
	v_add3_u32 v6, v6, v25, s27
	v_and_or_b32 v24, v6, s6, v24
	s_waitcnt lgkmcnt(5)
	v_bfe_u32 v6, v30, 16, 1
	v_add3_u32 v6, v30, v6, s27
	s_waitcnt lgkmcnt(4)
	v_bfe_u32 v25, v32, 16, 1
	v_lshrrev_b32_e32 v6, 16, v6
	v_add3_u32 v25, v32, v25, s27
	v_and_or_b32 v25, v25, s6, v6
	s_waitcnt lgkmcnt(3)
	v_bfe_u32 v6, v34, 16, 1
	v_add3_u32 v6, v34, v6, s27
	s_waitcnt lgkmcnt(2)
	v_bfe_u32 v26, v36, 16, 1
	v_lshrrev_b32_e32 v6, 16, v6
	v_add3_u32 v26, v36, v26, s27
	v_and_or_b32 v26, v26, s6, v6
	s_waitcnt lgkmcnt(1)
	v_bfe_u32 v6, v38, 16, 1
	v_add3_u32 v6, v38, v6, s27
	s_waitcnt lgkmcnt(0)
	v_bfe_u32 v27, v40, 16, 1
	v_lshrrev_b32_e32 v6, 16, v6
	v_add3_u32 v27, v40, v27, s27
	v_and_or_b32 v27, v27, s6, v6
	v_lshlrev_b32_e32 v6, 11, v8
	v_sub_u32_e32 v6, v19, v6
	v_and_b32_e32 v6, 0x2000, v6
	v_lshrrev_b32_e32 v8, 3, v23
	v_lshl_or_b32 v6, v9, 14, v6
	v_and_or_b32 v8, v8, 14, v14
	v_lshl_or_b32 v23, v8, 9, v6
	v_or_b32_e32 v6, v23, v18
	v_lshlrev_b32_e32 v206, 1, v6
	v_bfe_u32 v6, v29, 16, 1
	v_add3_u32 v6, v29, v6, s27
	v_bfe_u32 v8, v7, 16, 1
	v_lshrrev_b32_e32 v6, 16, v6
	v_add3_u32 v7, v7, v8, s27
	v_and_or_b32 v6, v7, s6, v6
	v_bfe_u32 v7, v31, 16, 1
	v_add3_u32 v7, v31, v7, s27
	v_bfe_u32 v8, v33, 16, 1
	v_lshrrev_b32_e32 v7, 16, v7
	v_add3_u32 v8, v33, v8, s27
	v_and_or_b32 v7, v8, s6, v7
	v_bfe_u32 v8, v35, 16, 1
	v_add3_u32 v8, v35, v8, s27
	v_bfe_u32 v9, v37, 16, 1
	v_lshrrev_b32_e32 v8, 16, v8
	v_add3_u32 v9, v37, v9, s27
	v_lshl_add_u64 v[42:43], v[4:5], 0, v[206:207]
	v_and_or_b32 v8, v9, s6, v8
	v_bfe_u32 v9, v39, 16, 1
	global_store_dwordx4 v[42:43], v[24:27], off sc0 sc1
	v_add3_u32 v9, v39, v9, s27
	v_lshrrev_b32_e32 v9, 16, v9
	v_bfe_u32 v24, v41, 16, 1
	v_add3_u32 v24, v41, v24, s27
	v_and_or_b32 v9, v24, s6, v9
	global_store_dwordx4 v[42:43], v[6:9], off offset:256 sc0 sc1
	ds_read2_b32 v[24:25], v12 offset0:49 offset1:57
	ds_read2_b32 v[26:27], v12 offset0:16 offset1:24
	ds_read2_b32 v[28:29], v12 offset0:82 offset1:90
	ds_read2_b32 v[30:31], v12 offset0:115 offset1:123
	ds_read2_b32 v[32:33], v12 offset0:148 offset1:156
	ds_read2_b32 v[34:35], v12 offset0:181 offset1:189
	ds_read2_b32 v[36:37], v12 offset0:214 offset1:222
	ds_read2_b32 v[38:39], v12 offset0:247 offset1:255
	s_waitcnt lgkmcnt(7)
	v_bfe_u32 v7, v24, 16, 1
	s_waitcnt lgkmcnt(6)
	v_bfe_u32 v6, v26, 16, 1
	v_add3_u32 v6, v26, v6, s27
	v_lshrrev_b32_e32 v6, 16, v6
	v_add3_u32 v7, v24, v7, s27
	v_and_or_b32 v6, v7, s6, v6
	s_waitcnt lgkmcnt(5)
	v_bfe_u32 v7, v28, 16, 1
	v_add3_u32 v7, v28, v7, s27
	s_waitcnt lgkmcnt(4)
	v_bfe_u32 v8, v30, 16, 1
	v_lshrrev_b32_e32 v7, 16, v7
	v_add3_u32 v8, v30, v8, s27
	v_and_or_b32 v7, v8, s6, v7
	s_waitcnt lgkmcnt(3)
	v_bfe_u32 v8, v32, 16, 1
	v_add3_u32 v8, v32, v8, s27
	s_waitcnt lgkmcnt(2)
	v_bfe_u32 v9, v34, 16, 1
	v_lshrrev_b32_e32 v8, 16, v8
	v_add3_u32 v9, v34, v9, s27
	v_and_or_b32 v8, v9, s6, v8
	s_waitcnt lgkmcnt(1)
	v_bfe_u32 v9, v36, 16, 1
	v_add3_u32 v9, v36, v9, s27
	s_waitcnt lgkmcnt(0)
	v_bfe_u32 v24, v38, 16, 1
	s_movk_i32 s28, 0x110
	v_lshrrev_b32_e32 v9, 16, v9
	v_add3_u32 v24, v38, v24, s27
	v_bitop3_b32 v206, v23, s28, v18 bitop3:0x36
	v_and_or_b32 v9, v24, s6, v9
	v_lshl_add_u64 v[40:41], v[206:207], 1, v[4:5]
	global_store_dwordx4 v[40:41], v[6:9], off sc0 sc1
	v_bfe_u32 v24, v39, 16, 1
	s_movk_i32 s28, 0x190
	v_bfe_u32 v6, v27, 16, 1
	v_add3_u32 v6, v27, v6, s27
	v_bfe_u32 v7, v25, 16, 1
	v_lshrrev_b32_e32 v6, 16, v6
	v_add3_u32 v7, v25, v7, s27
	v_and_or_b32 v6, v7, s6, v6
	v_bfe_u32 v7, v29, 16, 1
	v_add3_u32 v7, v29, v7, s27
	v_bfe_u32 v8, v31, 16, 1
	v_lshrrev_b32_e32 v7, 16, v7
	v_add3_u32 v8, v31, v8, s27
	v_and_or_b32 v7, v8, s6, v7
	v_bfe_u32 v8, v33, 16, 1
	v_add3_u32 v8, v33, v8, s27
	v_bfe_u32 v9, v35, 16, 1
	v_lshrrev_b32_e32 v8, 16, v8
	v_add3_u32 v9, v35, v9, s27
	v_and_or_b32 v8, v9, s6, v8
	v_bfe_u32 v9, v37, 16, 1
	v_add3_u32 v9, v37, v9, s27
	v_lshrrev_b32_e32 v9, 16, v9
	v_add3_u32 v24, v39, v24, s27
	v_bitop3_b32 v206, v23, s28, v18 bitop3:0x36
	v_and_or_b32 v9, v24, s6, v9
	v_lshl_add_u64 v[4:5], v[206:207], 1, v[4:5]
	global_store_dwordx4 v[4:5], v[6:9], off sc0 sc1
	s_waitcnt lgkmcnt(0)
	v_readlane_b32 s70, v251, 2
	v_readlane_b32 s71, v251, 3
	v_readlane_b32 s72, v251, 4
	v_readlane_b32 s73, v251, 5
	v_readlane_b32 s76, v251, 8
	v_readlane_b32 s77, v251, 9
	v_readlane_b32 s78, v251, 10
	v_readlane_b32 s79, v251, 11
	v_readlane_b32 s80, v251, 12
	v_readlane_b32 s81, v251, 13
	v_readlane_b32 s82, v251, 14
	v_readlane_b32 s83, v251, 15

; __device__ __forceinline__ void transpose_item(const float* W, int K, int N, bf16_t* WT, int ldw, LAS float* scr, int item, int lane) {
;     const int nblk = N / 32, kb = item / nblk, nb = item % nblk, k0 = 64 * kb, n0 = 32 * nb;
;     float tv[32];
; #pragma unroll
;     for (int i = 0; i < 32; ++i) { const int kk = 2 * i + (lane >> 5); tv[i] = W[(size_t)(k0 + kk) * N + n0 + (lane & 31)]; }
.LBB0_209:
	s_andn2_saveexec_b64 s[40:41], s[40:41]
	s_cbranch_execz .LBB0_211
	v_lshlrev_b32_e32 v23, 5, v8
	v_readlane_b32 s68, v251, 0
	v_sub_u32_e32 v23, v21, v23
	v_lshlrev_b64 v[6:7], 22, v[6:7]
	v_readlane_b32 s72, v251, 4
	v_readlane_b32 s73, v251, 5
	v_and_b32_e32 v24, 0x3e0, v23
	v_add_u32_e32 v9, 0xfc80, v9
	v_lshl_add_u64 v[6:7], s[72:73], 0, v[6:7]
	v_lshlrev_b32_e32 v206, 2, v24
	v_bfe_u32 v9, v9, 5, 11
	v_lshl_add_u64 v[6:7], v[6:7], 0, v[206:207]
	v_lshlrev_b32_e32 v206, 2, v2
	v_lshlrev_b32_e32 v24, 2, v17
	v_lshl_add_u64 v[6:7], v[6:7], 0, v[206:207]
	v_lshl_or_b32 v206, v9, 18, v24
	v_lshl_add_u64 v[6:7], v[6:7], 0, v[206:207]
	s_movk_i32 s28, 0x2000
	v_add_co_u32_e32 v24, vcc, s28, v6
	s_movk_i32 s28, 0x4000
	s_nop 0
	v_addc_co_u32_e32 v25, vcc, 0, v7, vcc
	global_load_dword v26, v[6:7], off
	global_load_dword v27, v[24:25], off
	v_add_co_u32_e32 v24, vcc, s28, v6
	s_mov_b32 s28, 0x8000
	s_nop 0
	v_addc_co_u32_e32 v25, vcc, 0, v7, vcc
	global_load_dword v28, v[24:25], off
	v_add_co_u32_e32 v24, vcc, s7, v6
	v_add_u32_e32 v23, v23, v13
	s_nop 0
	v_addc_co_u32_e32 v25, vcc, 0, v7, vcc
	global_load_dword v29, v[24:25], off
	v_add_co_u32_e32 v24, vcc, s28, v6
	s_mov_b32 s28, 0xa000
	s_nop 0
	v_addc_co_u32_e32 v25, vcc, 0, v7, vcc
	global_load_dword v30, v[24:25], off
	v_add_co_u32_e32 v24, vcc, s28, v6
	s_mov_b32 s28, 0xc000
	s_nop 0
	v_addc_co_u32_e32 v25, vcc, 0, v7, vcc
	global_load_dword v31, v[24:25], off
	v_add_co_u32_e32 v24, vcc, s28, v6
	s_mov_b32 s28, 0xe000
	s_nop 0
	v_addc_co_u32_e32 v25, vcc, 0, v7, vcc
	global_load_dword v32, v[24:25], off
	v_add_co_u32_e32 v24, vcc, s28, v6
	s_mov_b32 s28, 0x10000
	s_nop 0
	v_addc_co_u32_e32 v25, vcc, 0, v7, vcc
	global_load_dword v33, v[24:25], off
	v_add_co_u32_e32 v24, vcc, s28, v6
	s_mov_b32 s28, 0x12000
	s_nop 0
	v_addc_co_u32_e32 v25, vcc, 0, v7, vcc
	global_load_dword v34, v[24:25], off
	v_add_co_u32_e32 v24, vcc, s28, v6
	s_mov_b32 s28, 0x14000
	s_nop 0
	v_addc_co_u32_e32 v25, vcc, 0, v7, vcc
	global_load_dword v35, v[24:25], off
	v_add_co_u32_e32 v24, vcc, s28, v6
	s_mov_b32 s28, 0x16000
	s_nop 0
	v_addc_co_u32_e32 v25, vcc, 0, v7, vcc
	global_load_dword v36, v[24:25], off
	v_add_co_u32_e32 v24, vcc, s28, v6
	s_mov_b32 s28, 0x18000
	s_nop 0
	v_addc_co_u32_e32 v25, vcc, 0, v7, vcc
	global_load_dword v37, v[24:25], off
	v_add_co_u32_e32 v24, vcc, s28, v6
	s_mov_b32 s28, 0x1a000
	s_nop 0
	v_addc_co_u32_e32 v25, vcc, 0, v7, vcc
	global_load_dword v38, v[24:25], off
	v_add_co_u32_e32 v24, vcc, s28, v6
	s_mov_b32 s28, 0x1c000
	s_nop 0
	v_addc_co_u32_e32 v25, vcc, 0, v7, vcc
	global_load_dword v39, v[24:25], off
	v_add_co_u32_e32 v24, vcc, s28, v6
	s_mov_b32 s28, 0x20000
	s_nop 0
	v_addc_co_u32_e32 v25, vcc, 0, v7, vcc
	global_load_dword v40, v[24:25], off
	v_add_co_u32_e32 v24, vcc, s26, v6
	s_mov_b64 s[8:9], 0x380000
	s_nop 0
	v_addc_co_u32_e32 v25, vcc, 0, v7, vcc
	global_load_dword v41, v[24:25], off
	v_add_co_u32_e32 v24, vcc, s28, v6
	s_mov_b32 s28, 0x22000
	s_nop 0
	v_addc_co_u32_e32 v25, vcc, 0, v7, vcc
	global_load_dword v42, v[24:25], off
	v_add_co_u32_e32 v24, vcc, s28, v6
	s_mov_b32 s28, 0x24000
	s_nop 0
	v_addc_co_u32_e32 v25, vcc, 0, v7, vcc
	global_load_dword v43, v[24:25], off
	v_add_co_u32_e32 v24, vcc, s28, v6
	s_mov_b32 s28, 0x26000
	s_nop 0
	v_addc_co_u32_e32 v25, vcc, 0, v7, vcc
	global_load_dword v44, v[24:25], off
	v_add_co_u32_e32 v24, vcc, s28, v6
	s_mov_b32 s28, 0x28000
	s_nop 0
	v_addc_co_u32_e32 v25, vcc, 0, v7, vcc
	global_load_dword v45, v[24:25], off
	v_add_co_u32_e32 v24, vcc, s28, v6
	s_mov_b32 s28, 0x2a000
	s_nop 0
	v_addc_co_u32_e32 v25, vcc, 0, v7, vcc
	global_load_dword v46, v[24:25], off
	v_add_co_u32_e32 v24, vcc, s28, v6
	s_mov_b32 s28, 0x2c000
	s_nop 0
	v_addc_co_u32_e32 v25, vcc, 0, v7, vcc
	global_load_dword v47, v[24:25], off
	v_add_co_u32_e32 v24, vcc, s28, v6
	s_mov_b32 s28, 0x2e000
	s_nop 0
	v_addc_co_u32_e32 v25, vcc, 0, v7, vcc
	global_load_dword v48, v[24:25], off
	v_add_co_u32_e32 v24, vcc, s28, v6
	s_mov_b32 s28, 0x30000
	s_nop 0
	v_addc_co_u32_e32 v25, vcc, 0, v7, vcc
	global_load_dword v49, v[24:25], off
	v_add_co_u32_e32 v24, vcc, s28, v6
	s_mov_b32 s28, 0x32000
	s_nop 0
	v_addc_co_u32_e32 v25, vcc, 0, v7, vcc
	global_load_dword v50, v[24:25], off
	v_add_co_u32_e32 v24, vcc, s28, v6
	s_mov_b32 s28, 0x34000
	s_nop 0
	v_addc_co_u32_e32 v25, vcc, 0, v7, vcc
	global_load_dword v51, v[24:25], off
	v_add_co_u32_e32 v24, vcc, s28, v6
	s_mov_b32 s28, 0x36000
	s_nop 0
	v_addc_co_u32_e32 v25, vcc, 0, v7, vcc
	global_load_dword v52, v[24:25], off
	v_add_co_u32_e32 v24, vcc, s28, v6
	s_mov_b32 s28, 0x38000
	s_nop 0
	v_addc_co_u32_e32 v25, vcc, 0, v7, vcc
	global_load_dword v53, v[24:25], off
	v_add_co_u32_e32 v24, vcc, s28, v6
	s_mov_b32 s28, 0x3a000
	s_nop 0
	v_addc_co_u32_e32 v25, vcc, 0, v7, vcc
	global_load_dword v54, v[24:25], off
	v_add_co_u32_e32 v24, vcc, s28, v6
	s_mov_b32 s28, 0x3c000
	s_nop 0
	v_addc_co_u32_e32 v25, vcc, 0, v7, vcc
	global_load_dword v55, v[24:25], off
	v_add_co_u32_e32 v24, vcc, s28, v6
	s_mov_b32 s28, 0x3e000
	s_nop 0
	v_addc_co_u32_e32 v25, vcc, 0, v7, vcc
	v_add_co_u32_e32 v6, vcc, s28, v6
	global_load_dword v24, v[24:25], off
	s_nop 0
	v_addc_co_u32_e32 v7, vcc, 0, v7, vcc
	global_load_dword v6, v[6:7], off
	v_add_u32_e32 v7, 0x400, v11
	s_waitcnt vmcnt(0)
; #define LAS __attribute__((address_space(3)))
; __device__ __forceinline__ unsigned pk2(float lo, float hi) { return f2bf(lo) | (f2bf(hi) << 16); }
; __host__ __device__ __forceinline__ unsigned img_off(unsigned row, unsigned col, unsigned KT) { return (((row >> 8) * KT + (col >> 6)) << 14) + (((row >> 7) & 1u) << 13) + hl_off(row & 127u, col & 63u); }
; __host__ __device__ __forceinline__ unsigned wrow_img(unsigned n) { const unsigned p = n & 31u, rho = 16u * ((p >> 2) & 1u) + 4u * (p >> 3) + (p & 3u); return (n & ~31u) | rho; }
; __device__ __forceinline__ void transpose_item(const float* W, int K, int N, bf16_t* WT, int ldw, LAS float* scr, int item, int lane) {
;     ...
;     for (int i = 0; i < 32; ++i) { const int kk = 2 * i + (lane >> 5); scr[kk * 33 + (lane & 31)] = tv[i]; }
;     asm volatile("s_waitcnt lgkmcnt(0)" ::: "memory");
;     const int c = lane & 7;
; #pragma unroll
;     for (int j = 0; j < 4; ++j) { const int n = (lane >> 3) + 8 * j; const LAS float* s = scr + (8 * c) * 33 + n;
;         u32x4 o; o.x = pk2(s[0 * 33], s[1 * 33]); o.y = pk2(s[2 * 33], s[3 * 33]); o.z = pk2(s[4 * 33], s[5 * 33]); o.w = pk2(s[6 * 33], s[7 * 33]);
;         *(u32x4*)(WT + img_off(wrow_img((unsigned)(n0 + n)), (unsigned)(k0 + 8 * c), (unsigned)(K / 64))) = o; }
	ds_write2_b32 v11, v26, v27 offset1:66
	ds_write2_b32 v11, v28, v29 offset0:132 offset1:198
	ds_write2_b32 v7, v30, v31 offset0:8 offset1:74
	ds_write2_b32 v7, v32, v33 offset0:140 offset1:206
	v_add_u32_e32 v7, 0x800, v11
	ds_write2_b32 v7, v34, v35 offset0:16 offset1:82
	ds_write2_b32 v7, v36, v37 offset0:148 offset1:214
	v_add_u32_e32 v7, 0xc00, v11
	ds_write2_b32 v7, v38, v39 offset0:24 offset1:90
	ds_write2_b32 v7, v40, v41 offset0:156 offset1:222
	v_add_u32_e32 v7, 0x1000, v11
	ds_write2_b32 v7, v42, v43 offset0:32 offset1:98
	ds_write2_b32 v7, v44, v45 offset0:164 offset1:230
	v_add_u32_e32 v7, 0x1400, v11
	ds_write2_b32 v7, v46, v47 offset0:40 offset1:106
	ds_write2_b32 v7, v48, v49 offset0:172 offset1:238
	v_add_u32_e32 v7, 0x1800, v11
	ds_write2_b32 v7, v50, v51 offset0:48 offset1:114
	ds_write2_b32 v7, v52, v53 offset0:180 offset1:246
	v_add_u32_e32 v7, 0x1c00, v11
	ds_write2_b32 v7, v54, v55 offset0:56 offset1:122
	ds_write2_b32 v7, v24, v6 offset0:188 offset1:254
	v_lshlrev_b32_e32 v6, 1, v8
	v_sub_u32_e32 v6, v20, v6
	s_waitcnt lgkmcnt(0)
	v_and_b32_e32 v6, 48, v6
	v_add_u32_e32 v9, v9, v6
	ds_read2_b32 v[6:7], v12 offset0:33 offset1:41
	ds_read2_b32 v[28:29], v12 offset1:8
	ds_read2_b32 v[30:31], v12 offset0:66 offset1:74
	ds_read2_b32 v[32:33], v12 offset0:99 offset1:107
	ds_read2_b32 v[34:35], v12 offset0:132 offset1:140
	ds_read2_b32 v[36:37], v12 offset0:165 offset1:173
	ds_read2_b32 v[38:39], v12 offset0:198 offset1:206
	ds_read2_b32 v[40:41], v12 offset0:231 offset1:239
	s_waitcnt lgkmcnt(7)
	v_bfe_u32 v25, v6, 16, 1
	s_waitcnt lgkmcnt(6)
	v_bfe_u32 v24, v28, 16, 1
	v_add3_u32 v24, v28, v24, s27
	v_lshrrev_b32_e32 v24, 16, v24
	v_add3_u32 v6, v6, v25, s27
	v_and_or_b32 v24, v6, s6, v24
	s_waitcnt lgkmcnt(5)
	v_bfe_u32 v6, v30, 16, 1
	v_add3_u32 v6, v30, v6, s27
	s_waitcnt lgkmcnt(4)
	v_bfe_u32 v25, v32, 16, 1
	v_lshrrev_b32_e32 v6, 16, v6
	v_add3_u32 v25, v32, v25, s27
	v_and_or_b32 v25, v25, s6, v6
	s_waitcnt lgkmcnt(3)
	v_bfe_u32 v6, v34, 16, 1
	v_add3_u32 v6, v34, v6, s27
	s_waitcnt lgkmcnt(2)
	v_bfe_u32 v26, v36, 16, 1
	v_lshrrev_b32_e32 v6, 16, v6
	v_add3_u32 v26, v36, v26, s27
	v_and_or_b32 v26, v26, s6, v6
	s_waitcnt lgkmcnt(1)
	v_bfe_u32 v6, v38, 16, 1
	v_add3_u32 v6, v38, v6, s27
	s_waitcnt lgkmcnt(0)
	v_bfe_u32 v27, v40, 16, 1
	v_lshrrev_b32_e32 v6, 16, v6
	v_add3_u32 v27, v40, v27, s27
	v_and_or_b32 v27, v27, s6, v6
	v_lshlrev_b32_e32 v6, 11, v8
	v_sub_u32_e32 v6, v19, v6
	v_and_b32_e32 v6, 0x2000, v6
	v_lshrrev_b32_e32 v8, 3, v23
	v_lshl_or_b32 v6, v9, 14, v6
	v_and_or_b32 v8, v8, 14, v14
	v_lshl_or_b32 v23, v8, 9, v6
	v_or_b32_e32 v6, v23, v18
	v_lshlrev_b32_e32 v206, 1, v6
	v_bfe_u32 v6, v29, 16, 1
	v_add3_u32 v6, v29, v6, s27
	v_bfe_u32 v8, v7, 16, 1
	v_lshrrev_b32_e32 v6, 16, v6
	v_add3_u32 v7, v7, v8, s27
	v_and_or_b32 v6, v7, s6, v6
	v_bfe_u32 v7, v31, 16, 1
	v_add3_u32 v7, v31, v7, s27
	v_bfe_u32 v8, v33, 16, 1
	v_lshrrev_b32_e32 v7, 16, v7
	v_add3_u32 v8, v33, v8, s27
	v_and_or_b32 v7, v8, s6, v7
	v_bfe_u32 v8, v35, 16, 1
	v_add3_u32 v8, v35, v8, s27
	v_bfe_u32 v9, v37, 16, 1
	v_lshl_add_u64 v[4:5], v[4:5], 0, s[8:9]
	v_lshrrev_b32_e32 v8, 16, v8
	v_add3_u32 v9, v37, v9, s27
	v_lshl_add_u64 v[42:43], v[4:5], 0, v[206:207]
	v_and_or_b32 v8, v9, s6, v8
	v_bfe_u32 v9, v39, 16, 1
	global_store_dwordx4 v[42:43], v[24:27], off sc0 sc1
	v_add3_u32 v9, v39, v9, s27
	v_lshrrev_b32_e32 v9, 16, v9
	v_bfe_u32 v24, v41, 16, 1
	v_add3_u32 v24, v41, v24, s27
	v_and_or_b32 v9, v24, s6, v9
	global_store_dwordx4 v[42:43], v[6:9], off offset:256 sc0 sc1
	ds_read2_b32 v[24:25], v12 offset0:49 offset1:57
	ds_read2_b32 v[26:27], v12 offset0:16 offset1:24
	ds_read2_b32 v[28:29], v12 offset0:82 offset1:90
	ds_read2_b32 v[30:31], v12 offset0:115 offset1:123
	ds_read2_b32 v[32:33], v12 offset0:148 offset1:156
	ds_read2_b32 v[34:35], v12 offset0:181 offset1:189
	ds_read2_b32 v[36:37], v12 offset0:214 offset1:222
	ds_read2_b32 v[38:39], v12 offset0:247 offset1:255
	s_waitcnt lgkmcnt(7)
	v_bfe_u32 v7, v24, 16, 1
	s_waitcnt lgkmcnt(6)
	v_bfe_u32 v6, v26, 16, 1
	v_add3_u32 v6, v26, v6, s27
	v_lshrrev_b32_e32 v6, 16, v6
	v_add3_u32 v7, v24, v7, s27
	v_and_or_b32 v6, v7, s6, v6
	s_waitcnt lgkmcnt(5)
	v_bfe_u32 v7, v28, 16, 1
	v_add3_u32 v7, v28, v7, s27
	s_waitcnt lgkmcnt(4)
	v_bfe_u32 v8, v30, 16, 1
	v_lshrrev_b32_e32 v7, 16, v7
	v_add3_u32 v8, v30, v8, s27
	v_and_or_b32 v7, v8, s6, v7
	s_waitcnt lgkmcnt(3)
	v_bfe_u32 v8, v32, 16, 1
	v_add3_u32 v8, v32, v8, s27
	s_waitcnt lgkmcnt(2)
	v_bfe_u32 v9, v34, 16, 1
	v_lshrrev_b32_e32 v8, 16, v8
	v_add3_u32 v9, v34, v9, s27
	v_and_or_b32 v8, v9, s6, v8
	s_waitcnt lgkmcnt(1)
	v_bfe_u32 v9, v36, 16, 1
	v_add3_u32 v9, v36, v9, s27
	s_waitcnt lgkmcnt(0)
	v_bfe_u32 v24, v38, 16, 1
	s_movk_i32 s28, 0x110
	v_lshrrev_b32_e32 v9, 16, v9
	v_add3_u32 v24, v38, v24, s27
	v_bitop3_b32 v206, v23, s28, v18 bitop3:0x36
	v_and_or_b32 v9, v24, s6, v9
	v_lshl_add_u64 v[40:41], v[206:207], 1, v[4:5]
	global_store_dwordx4 v[40:41], v[6:9], off sc0 sc1
	v_bfe_u32 v24, v39, 16, 1
	s_movk_i32 s28, 0x190
	v_bfe_u32 v6, v27, 16, 1
	v_add3_u32 v6, v27, v6, s27
	v_bfe_u32 v7, v25, 16, 1
	v_lshrrev_b32_e32 v6, 16, v6
	v_add3_u32 v7, v25, v7, s27
	v_and_or_b32 v6, v7, s6, v6
	v_bfe_u32 v7, v29, 16, 1
	v_add3_u32 v7, v29, v7, s27
	v_bfe_u32 v8, v31, 16, 1
	v_lshrrev_b32_e32 v7, 16, v7
	v_add3_u32 v8, v31, v8, s27
	v_and_or_b32 v7, v8, s6, v7
	v_bfe_u32 v8, v33, 16, 1
	v_add3_u32 v8, v33, v8, s27
	v_bfe_u32 v9, v35, 16, 1
	v_lshrrev_b32_e32 v8, 16, v8
	v_add3_u32 v9, v35, v9, s27
	v_and_or_b32 v8, v9, s6, v8
	v_bfe_u32 v9, v37, 16, 1
	v_add3_u32 v9, v37, v9, s27
	v_lshrrev_b32_e32 v9, 16, v9
	v_add3_u32 v24, v39, v24, s27
	v_bitop3_b32 v206, v23, s28, v18 bitop3:0x36
	v_and_or_b32 v9, v24, s6, v9
	v_lshl_add_u64 v[4:5], v[206:207], 1, v[4:5]
	global_store_dwordx4 v[4:5], v[6:9], off sc0 sc1
	s_waitcnt lgkmcnt(0)
	v_readlane_b32 s69, v251, 1
	v_readlane_b32 s70, v251, 2
	v_readlane_b32 s71, v251, 3
	v_readlane_b32 s74, v251, 6
	v_readlane_b32 s75, v251, 7
	v_readlane_b32 s76, v251, 8
	v_readlane_b32 s77, v251, 9
	v_readlane_b32 s78, v251, 10
	v_readlane_b32 s79, v251, 11
	v_readlane_b32 s80, v251, 12
	v_readlane_b32 s81, v251, 13
	v_readlane_b32 s82, v251, 14
	v_readlane_b32 s83, v251, 15

; __device__ __forceinline__ void transpose_item(const float* W, int K, int N, bf16_t* WT, int ldw, LAS float* scr, int item, int lane) {
;     const int nblk = N / 32, kb = item / nblk, nb = item % nblk, k0 = 64 * kb, n0 = 32 * nb;
;     float tv[32];
; #pragma unroll
;     for (int i = 0; i < 32; ++i) { const int kk = 2 * i + (lane >> 5); tv[i] = W[(size_t)(k0 + kk) * N + n0 + (lane & 31)]; }
; __device__ __forceinline__ void transpose_layers(const Args& a, LAS unsigned char* lds, int l_lo, int l_hi, int wb, int nwb) {
;     ...
;         if (r < I_IN) { transpose_item(a.in[8] + (size_t)l * DM * DIN, DM, DIN, (bf16_t*)(wl + WT_IN), DM, scr, r, lane); continue; } r -= I_IN;
.LBB0_212:
	s_andn2_saveexec_b64 s[38:39], s[38:39]
	s_cbranch_execz .LBB0_201
	s_mov_b32 s28, s10
	s_mov_b64 s[34:35], s[12:13]
	v_readlane_b32 s8, v254, 23
	v_mul_hi_i32_i24_e32 v7, 0x700000, v6
	v_mul_i32_i24_e32 v6, 0x700000, v6
	v_readlane_b32 s9, v254, 24
	v_lshlrev_b32_e32 v206, 2, v2
	v_readlane_b32 s10, v254, 25
	v_lshl_add_u64 v[24:25], s[8:9], 0, v[6:7]
	v_mul_i32_i24_e32 v6, 0x4925, v9
	v_mov_b32_e32 v7, 4
	v_ashrrev_i16_sdwa v7, v7, v6 dst_sel:DWORD dst_unused:UNUSED_PAD src0_sel:DWORD src1_sel:WORD_1
	v_lshrrev_b32_e32 v6, 31, v6
	v_add_u16_e32 v6, v7, v6
	v_bfe_i32 v26, v6, 0, 16
	v_mul_lo_u16_e32 v6, 56, v6
	v_sub_u16_e32 v23, v9, v6
	v_mov_b32_e32 v6, 5
	v_lshlrev_b32_sdwa v6, v6, sext(v23) dst_sel:DWORD dst_unused:UNUSED_PAD src0_sel:DWORD src1_sel:WORD_0
	v_lshl_or_b32 v27, v26, 6, v10
	v_ashrrev_i32_e32 v7, 31, v6
	v_lshl_add_u64 v[8:9], v[6:7], 2, v[24:25]
	v_mul_i32_i24_e32 v24, 0x700, v27
	v_lshl_add_u64 v[8:9], v[8:9], 0, v[206:207]
	v_ashrrev_i32_e32 v25, 31, v24
	s_mov_b32 s10, s28
	v_lshl_add_u64 v[8:9], v[24:25], 2, v[8:9]
	s_movk_i32 s28, 0x3000
	v_add_co_u32_e32 v24, vcc, s28, v8
	s_movk_i32 s28, 0x7000
	s_nop 0
	v_addc_co_u32_e32 v25, vcc, 0, v9, vcc
	global_load_dword v27, v[24:25], off offset:2048
	v_add_co_u32_e32 v24, vcc, s28, v8
	s_mov_b32 s28, 0xa000
	s_nop 0
	v_addc_co_u32_e32 v25, vcc, 0, v9, vcc
	global_load_dword v7, v[8:9], off
	global_load_dword v28, v[24:25], off
	v_add_co_u32_e32 v24, vcc, s28, v8
	s_mov_b32 s28, 0xe000
	s_nop 0
	v_addc_co_u32_e32 v25, vcc, 0, v9, vcc
	global_load_dword v29, v[24:25], off offset:2048
	v_add_co_u32_e32 v24, vcc, s28, v8
	s_mov_b32 s28, 0x11000
	s_nop 0
	v_addc_co_u32_e32 v25, vcc, 0, v9, vcc
	global_load_dword v30, v[24:25], off
	v_add_co_u32_e32 v24, vcc, s28, v8
	s_mov_b32 s28, 0x15000
	s_nop 0
	v_addc_co_u32_e32 v25, vcc, 0, v9, vcc
	global_load_dword v31, v[24:25], off offset:2048
	v_add_co_u32_e32 v24, vcc, s28, v8
	s_mov_b32 s28, 0x18000
	s_nop 0
	v_addc_co_u32_e32 v25, vcc, 0, v9, vcc
	global_load_dword v32, v[24:25], off
	v_add_co_u32_e32 v24, vcc, s28, v8
	s_mov_b32 s28, 0x1c000
	s_nop 0
	v_addc_co_u32_e32 v25, vcc, 0, v9, vcc
	global_load_dword v33, v[24:25], off offset:2048
	v_add_co_u32_e32 v24, vcc, s28, v8
	s_mov_b32 s28, 0x1f000
	s_nop 0
	v_addc_co_u32_e32 v25, vcc, 0, v9, vcc
	global_load_dword v34, v[24:25], off
	v_add_co_u32_e32 v24, vcc, s28, v8
	s_mov_b32 s28, 0x23000
	s_nop 0
	v_addc_co_u32_e32 v25, vcc, 0, v9, vcc
	global_load_dword v35, v[24:25], off offset:2048
	v_add_co_u32_e32 v24, vcc, s28, v8
	s_mov_b32 s28, 0x26000
	s_nop 0
	v_addc_co_u32_e32 v25, vcc, 0, v9, vcc
	global_load_dword v36, v[24:25], off
	v_add_co_u32_e32 v24, vcc, s28, v8
	s_mov_b32 s28, 0x2a000
	s_nop 0
	v_addc_co_u32_e32 v25, vcc, 0, v9, vcc
	global_load_dword v37, v[24:25], off offset:2048
	v_add_co_u32_e32 v24, vcc, s28, v8
	s_mov_b32 s28, 0x2d000
	s_nop 0
	v_addc_co_u32_e32 v25, vcc, 0, v9, vcc
	global_load_dword v38, v[24:25], off
	v_add_co_u32_e32 v24, vcc, s28, v8
	s_mov_b32 s28, 0x31000
	s_nop 0
	v_addc_co_u32_e32 v25, vcc, 0, v9, vcc
	global_load_dword v39, v[24:25], off offset:2048
	v_add_co_u32_e32 v24, vcc, s28, v8
	s_mov_b32 s28, 0x34000
	s_nop 0
	v_addc_co_u32_e32 v25, vcc, 0, v9, vcc
	global_load_dword v40, v[24:25], off
	v_add_co_u32_e32 v24, vcc, s28, v8
	s_mov_b32 s28, 0x38000
	s_nop 0
	v_addc_co_u32_e32 v25, vcc, 0, v9, vcc
	global_load_dword v41, v[24:25], off offset:2048
	v_add_co_u32_e32 v24, vcc, s28, v8
	s_mov_b32 s28, 0x3b000
	s_nop 0
	v_addc_co_u32_e32 v25, vcc, 0, v9, vcc
	global_load_dword v42, v[24:25], off
	v_add_co_u32_e32 v24, vcc, s28, v8
	s_mov_b32 s28, 0x3f000
	s_nop 0
	v_addc_co_u32_e32 v25, vcc, 0, v9, vcc
	global_load_dword v43, v[24:25], off offset:2048
	v_add_co_u32_e32 v24, vcc, s28, v8
	s_mov_b32 s28, 0x42000
	s_nop 0
	v_addc_co_u32_e32 v25, vcc, 0, v9, vcc
	global_load_dword v44, v[24:25], off
	v_add_co_u32_e32 v24, vcc, s28, v8
	s_mov_b32 s28, 0x46000
	s_nop 0
	v_addc_co_u32_e32 v25, vcc, 0, v9, vcc
	global_load_dword v45, v[24:25], off offset:2048
	v_add_co_u32_e32 v24, vcc, s28, v8
	s_mov_b32 s28, 0x49000
	s_nop 0
	v_addc_co_u32_e32 v25, vcc, 0, v9, vcc
	global_load_dword v46, v[24:25], off
	v_add_co_u32_e32 v24, vcc, s28, v8
	s_mov_b32 s28, 0x4d000
	s_nop 0
	v_addc_co_u32_e32 v25, vcc, 0, v9, vcc
	global_load_dword v47, v[24:25], off offset:2048
	v_add_co_u32_e32 v24, vcc, s28, v8
	s_mov_b32 s28, 0x50000
	s_nop 0
	v_addc_co_u32_e32 v25, vcc, 0, v9, vcc
	global_load_dword v48, v[24:25], off
	v_add_co_u32_e32 v24, vcc, s28, v8
	s_mov_b32 s28, 0x54000
	s_nop 0
	v_addc_co_u32_e32 v25, vcc, 0, v9, vcc
	global_load_dword v49, v[24:25], off offset:2048
	v_add_co_u32_e32 v24, vcc, s28, v8
	s_mov_b32 s28, 0x57000
	s_nop 0
	v_addc_co_u32_e32 v25, vcc, 0, v9, vcc
	global_load_dword v50, v[24:25], off
	v_add_co_u32_e32 v24, vcc, s28, v8
	s_mov_b32 s28, 0x5b000
	s_nop 0
	v_addc_co_u32_e32 v25, vcc, 0, v9, vcc
	global_load_dword v51, v[24:25], off offset:2048
	v_add_co_u32_e32 v24, vcc, s28, v8
	s_mov_b32 s28, 0x5e000
	s_nop 0
	v_addc_co_u32_e32 v25, vcc, 0, v9, vcc
	global_load_dword v52, v[24:25], off
	v_add_co_u32_e32 v24, vcc, s28, v8
	s_mov_b32 s28, 0x62000
	s_nop 0
	v_addc_co_u32_e32 v25, vcc, 0, v9, vcc
	global_load_dword v53, v[24:25], off offset:2048
	v_add_co_u32_e32 v24, vcc, s28, v8
	s_mov_b32 s28, 0x65000
	s_nop 0
	v_addc_co_u32_e32 v25, vcc, 0, v9, vcc
	global_load_dword v54, v[24:25], off
	v_add_co_u32_e32 v24, vcc, s28, v8
	s_mov_b32 s28, 0x69000
	s_nop 0
	v_addc_co_u32_e32 v25, vcc, 0, v9, vcc
	global_load_dword v55, v[24:25], off offset:2048
	v_add_co_u32_e32 v24, vcc, s28, v8
	v_readlane_b32 s12, v254, 27
	s_nop 0
	v_addc_co_u32_e32 v25, vcc, 0, v9, vcc
	v_add_co_u32_e32 v8, vcc, s31, v8
	global_load_dword v24, v[24:25], off
	s_nop 0
	v_addc_co_u32_e32 v9, vcc, 0, v9, vcc
	global_load_dword v8, v[8:9], off offset:2048
	s_waitcnt vmcnt(0)
; #define LAS __attribute__((address_space(3)))
; __device__ __forceinline__ unsigned pk2(float lo, float hi) { return f2bf(lo) | (f2bf(hi) << 16); }
; __host__ __device__ __forceinline__ unsigned img_off(unsigned row, unsigned col, unsigned KT) { return (((row >> 8) * KT + (col >> 6)) << 14) + (((row >> 7) & 1u) << 13) + hl_off(row & 127u, col & 63u); }
; __host__ __device__ __forceinline__ unsigned wrow_img(unsigned n) { const unsigned p = n & 31u, rho = 16u * ((p >> 2) & 1u) + 4u * (p >> 3) + (p & 3u); return (n & ~31u) | rho; }
; __device__ __forceinline__ void transpose_item(const float* W, int K, int N, bf16_t* WT, int ldw, LAS float* scr, int item, int lane) {
;     ...
;     for (int i = 0; i < 32; ++i) { const int kk = 2 * i + (lane >> 5); scr[kk * 33 + (lane & 31)] = tv[i]; }
;     asm volatile("s_waitcnt lgkmcnt(0)" ::: "memory");
;     const int c = lane & 7;
; #pragma unroll
;     for (int j = 0; j < 4; ++j) { const int n = (lane >> 3) + 8 * j; const LAS float* s = scr + (8 * c) * 33 + n;
;         u32x4 o; o.x = pk2(s[0 * 33], s[1 * 33]); o.y = pk2(s[2 * 33], s[3 * 33]); o.z = pk2(s[4 * 33], s[5 * 33]); o.w = pk2(s[6 * 33], s[7 * 33]);
;         *(u32x4*)(WT + img_off(wrow_img((unsigned)(n0 + n)), (unsigned)(k0 + 8 * c), (unsigned)(K / 64))) = o; }
	ds_write2_b32 v11, v7, v27 offset1:66
	ds_write2_b32 v11, v28, v29 offset0:132 offset1:198
	v_add_u32_e32 v7, 0x400, v11
	ds_write2_b32 v7, v30, v31 offset0:8 offset1:74
	ds_write2_b32 v7, v32, v33 offset0:140 offset1:206
	v_add_u32_e32 v7, 0x800, v11
	ds_write2_b32 v7, v34, v35 offset0:16 offset1:82
	ds_write2_b32 v7, v36, v37 offset0:148 offset1:214
	v_add_u32_e32 v7, 0xc00, v11
	ds_write2_b32 v7, v38, v39 offset0:24 offset1:90
	ds_write2_b32 v7, v40, v41 offset0:156 offset1:222
	v_add_u32_e32 v7, 0x1000, v11
	ds_write2_b32 v7, v42, v43 offset0:32 offset1:98
	ds_write2_b32 v7, v44, v45 offset0:164 offset1:230
	v_add_u32_e32 v7, 0x1400, v11
	ds_write2_b32 v7, v46, v47 offset0:40 offset1:106
	ds_write2_b32 v7, v48, v49 offset0:172 offset1:238
	v_add_u32_e32 v7, 0x1800, v11
	ds_write2_b32 v7, v50, v51 offset0:48 offset1:114
	ds_write2_b32 v7, v52, v53 offset0:180 offset1:246
	v_add_u32_e32 v7, 0x1c00, v11
	ds_write2_b32 v7, v54, v55 offset0:56 offset1:122
	ds_write2_b32 v7, v24, v8 offset0:188 offset1:254
	v_or_b32_e32 v40, v16, v6
	v_lshlrev_b32_sdwa v6, v1, sext(v23) dst_sel:DWORD dst_unused:UNUSED_PAD src0_sel:DWORD src1_sel:WORD_0
	s_waitcnt lgkmcnt(0)
	v_and_b32_e32 v6, 0x3fff0, v6
	v_add_u32_e32 v41, v6, v26
	ds_read2_b32 v[24:25], v12 offset0:33 offset1:41
	ds_read2_b32 v[26:27], v12 offset1:8
	ds_read2_b32 v[28:29], v12 offset0:66 offset1:74
	ds_read2_b32 v[30:31], v12 offset0:99 offset1:107
	ds_read2_b32 v[32:33], v12 offset0:132 offset1:140
	ds_read2_b32 v[34:35], v12 offset0:165 offset1:173
	ds_read2_b32 v[36:37], v12 offset0:198 offset1:206
	ds_read2_b32 v[38:39], v12 offset0:231 offset1:239
	s_waitcnt lgkmcnt(7)
	v_bfe_u32 v7, v24, 16, 1
	s_waitcnt lgkmcnt(6)
	v_bfe_u32 v6, v26, 16, 1
	v_add3_u32 v6, v26, v6, s27
	v_lshrrev_b32_e32 v6, 16, v6
	v_add3_u32 v7, v24, v7, s27
	v_and_or_b32 v6, v7, s6, v6
	s_waitcnt lgkmcnt(5)
	v_bfe_u32 v7, v28, 16, 1
	v_add3_u32 v7, v28, v7, s27
	s_waitcnt lgkmcnt(4)
	v_bfe_u32 v8, v30, 16, 1
	v_lshrrev_b32_e32 v7, 16, v7
	v_add3_u32 v8, v30, v8, s27
	v_and_or_b32 v7, v8, s6, v7
	s_waitcnt lgkmcnt(3)
	v_bfe_u32 v8, v32, 16, 1
	v_add3_u32 v8, v32, v8, s27
	s_waitcnt lgkmcnt(2)
	v_bfe_u32 v9, v34, 16, 1
	v_lshrrev_b32_e32 v8, 16, v8
	v_add3_u32 v9, v34, v9, s27
	v_and_or_b32 v8, v9, s6, v8
	s_waitcnt lgkmcnt(1)
	v_bfe_u32 v9, v36, 16, 1
	v_add3_u32 v9, v36, v9, s27
	s_waitcnt lgkmcnt(0)
	v_bfe_u32 v24, v38, 16, 1
	v_lshrrev_b32_e32 v9, 16, v9
	v_add3_u32 v24, v38, v24, s27
	v_and_or_b32 v9, v24, s6, v9
	v_mov_b32_e32 v24, 11
	v_lshlrev_b32_sdwa v23, v24, sext(v23) dst_sel:DWORD dst_unused:UNUSED_PAD src0_sel:DWORD src1_sel:WORD_0
	v_lshrrev_b32_e32 v24, 3, v40
	v_lshlrev_b32_e32 v26, 5, v16
	v_and_b32_e32 v23, 0x2000, v23
	v_and_or_b32 v24, v24, 14, v14
	v_and_b32_e32 v26, 0x60, v26
	v_lshl_or_b32 v23, v41, 14, v23
	v_lshl_or_b32 v24, v24, 9, v26
	v_or3_b32 v206, v24, v23, v15
	v_lshl_add_u64 v[40:41], v[206:207], 1, v[4:5]
	global_store_dwordx4 v[40:41], v[6:9], off sc0 sc1
	v_bfe_u32 v23, v39, 16, 1
	v_add3_u32 v23, v39, v23, s27
	v_bfe_u32 v6, v27, 16, 1
	v_add3_u32 v6, v27, v6, s27
	v_bfe_u32 v7, v25, 16, 1
	v_lshrrev_b32_e32 v6, 16, v6
	v_add3_u32 v7, v25, v7, s27
	v_and_or_b32 v6, v7, s6, v6
	v_bfe_u32 v7, v29, 16, 1
	v_add3_u32 v7, v29, v7, s27
	v_bfe_u32 v8, v31, 16, 1
	v_lshrrev_b32_e32 v7, 16, v7
	v_add3_u32 v8, v31, v8, s27
	v_and_or_b32 v7, v8, s6, v7
	v_bfe_u32 v8, v33, 16, 1
	v_add3_u32 v8, v33, v8, s27
	v_bfe_u32 v9, v35, 16, 1
	v_lshrrev_b32_e32 v8, 16, v8
	v_add3_u32 v9, v35, v9, s27
	v_and_or_b32 v8, v9, s6, v8
	v_bfe_u32 v9, v37, 16, 1
	v_add3_u32 v9, v37, v9, s27
	v_lshrrev_b32_e32 v9, 16, v9
	v_and_or_b32 v9, v23, s6, v9
	global_store_dwordx4 v[40:41], v[6:9], off offset:256 sc0 sc1
	ds_read2_b32 v[24:25], v12 offset0:49 offset1:57
	ds_read2_b32 v[26:27], v12 offset0:16 offset1:24
	ds_read2_b32 v[28:29], v12 offset0:82 offset1:90
	ds_read2_b32 v[30:31], v12 offset0:115 offset1:123
	ds_read2_b32 v[32:33], v12 offset0:148 offset1:156
	ds_read2_b32 v[34:35], v12 offset0:181 offset1:189
	ds_read2_b32 v[36:37], v12 offset0:214 offset1:222
	ds_read2_b32 v[38:39], v12 offset0:247 offset1:255
	s_waitcnt lgkmcnt(7)
	v_bfe_u32 v7, v24, 16, 1
	s_waitcnt lgkmcnt(6)
	v_bfe_u32 v6, v26, 16, 1
	v_add3_u32 v6, v26, v6, s27
	v_lshrrev_b32_e32 v6, 16, v6
	v_add3_u32 v7, v24, v7, s27
	v_and_or_b32 v6, v7, s6, v6
	s_waitcnt lgkmcnt(5)
	v_bfe_u32 v7, v28, 16, 1
	v_add3_u32 v7, v28, v7, s27
	s_waitcnt lgkmcnt(4)
	v_bfe_u32 v8, v30, 16, 1
	v_lshrrev_b32_e32 v7, 16, v7
	v_add3_u32 v8, v30, v8, s27
	v_and_or_b32 v7, v8, s6, v7
	s_waitcnt lgkmcnt(3)
	v_bfe_u32 v8, v32, 16, 1
	v_add3_u32 v8, v32, v8, s27
	s_waitcnt lgkmcnt(2)
	v_bfe_u32 v9, v34, 16, 1
	v_lshrrev_b32_e32 v8, 16, v8
	v_add3_u32 v9, v34, v9, s27
	v_xor_b32_e32 v206, 16, v206
	v_and_or_b32 v8, v9, s6, v8
	s_waitcnt lgkmcnt(1)
	v_bfe_u32 v9, v36, 16, 1
	v_lshl_add_u64 v[40:41], v[206:207], 1, v[4:5]
	v_bfe_u32 v4, v27, 16, 1
	v_add3_u32 v9, v36, v9, s27
	s_waitcnt lgkmcnt(0)
	v_bfe_u32 v23, v38, 16, 1
	v_add3_u32 v4, v27, v4, s27
	v_bfe_u32 v5, v25, 16, 1
	v_lshrrev_b32_e32 v9, 16, v9
	v_add3_u32 v23, v38, v23, s27
	v_lshrrev_b32_e32 v4, 16, v4
	v_add3_u32 v5, v25, v5, s27
	v_and_or_b32 v9, v23, s6, v9
	v_and_or_b32 v4, v5, s6, v4
	v_bfe_u32 v5, v29, 16, 1
	global_store_dwordx4 v[40:41], v[6:9], off offset:512 sc0 sc1
	v_add3_u32 v5, v29, v5, s27
	v_lshrrev_b32_e32 v5, 16, v5
	v_bfe_u32 v6, v31, 16, 1
	v_add3_u32 v6, v31, v6, s27
	v_and_or_b32 v5, v6, s6, v5
	v_bfe_u32 v6, v33, 16, 1
	v_add3_u32 v6, v33, v6, s27
	v_bfe_u32 v7, v35, 16, 1
	v_lshrrev_b32_e32 v6, 16, v6
	v_add3_u32 v7, v35, v7, s27
	v_and_or_b32 v6, v7, s6, v6
	v_bfe_u32 v7, v37, 16, 1
	v_add3_u32 v7, v37, v7, s27
	v_bfe_u32 v8, v39, 16, 1
	v_lshrrev_b32_e32 v7, 16, v7
	v_add3_u32 v8, v39, v8, s27
	v_and_or_b32 v7, v8, s6, v7
	global_store_dwordx4 v[40:41], v[4:7], off offset:768 sc0 sc1
	s_waitcnt lgkmcnt(0)
	v_readlane_b32 s13, v254, 28
	s_mov_b64 s[12:13], s[34:35]
	v_readlane_b32 s11, v254, 26
	v_readlane_b32 s14, v254, 29
	v_readlane_b32 s15, v254, 30
	v_readlane_b32 s16, v254, 31
	v_readlane_b32 s17, v254, 32
	v_readlane_b32 s18, v254, 33
	v_readlane_b32 s19, v254, 34
	v_readlane_b32 s20, v254, 35
	v_readlane_b32 s21, v254, 36
	v_readlane_b32 s22, v254, 37
	v_readlane_b32 s23, v254, 38
	s_branch .LBB0_201
